# Fourier latent items (row+column): issue both load rounds (4 loads) at once instead of two load-wait-write rounds
# baseline (speedup 1.0000x reference)
.LBB0_598:
	s_lshl_b32 s0, s5, 4
	s_and_b32 s10, s0, 0xffffffc0
	s_lshl_b32 s0, s5, 8
	s_and_b32 s11, s0, 0x300
	s_addk_i32 s10, 0x2000
	s_lshl_b32 s0, s11, 1
	s_add_u32 s0, s58, s0
	s_addc_u32 s1, s59, 0
	s_mov_b64 s[8:9], 0
	v_mov_b32_e32 v5, v9
	v_mov_b32_e32 v11, v101
	v_mov_b32_e32 v12, v8
	v_and_b32_e32 v13, 62, v5
	v_or_b32_e32 v14, s10, v13
	v_ashrrev_i32_e32 v15, 31, v14
	v_and_b32_e32 v22, 0x80, v11
	v_lshlrev_b64 v[14:15], 11, v[14:15]
	v_and_b32_e32 v23, 0x78, v11
	v_lshlrev_b32_e32 v0, 1, v22
	v_lshl_add_u64 v[14:15], s[0:1], 0, v[14:15]
	v_lshl_add_u64 v[14:15], v[14:15], 0, v[0:1]
	v_lshlrev_b32_e32 v0, 1, v23
	v_lshl_add_u64 v[36:37], v[14:15], 0, v[0:1]
	global_load_dwordx4 v[14:17], v[36:37], off
	global_load_dwordx4 v[18:21], v[36:37], off offset:2048
	global_load_dwordx4 v[28:31], v[36:37], off offset:256
	global_load_dwordx4 v[32:35], v[36:37], off offset:2304
	v_mad_u32_u24 v0, v23, s3, 0
	v_lshlrev_b32_e32 v13, 1, v13
	v_add3_u32 v0, v0, v22, v13
	v_add_u32_e32 v13, 0x400, v0
	v_add_u32_e32 v26, 0x80, v0
	v_add_u32_e32 v27, 0x480, v0
	s_waitcnt vmcnt(3)
	v_and_b32_e32 v22, 0xffff, v14
	v_lshrrev_b32_e32 v14, 16, v14
	v_and_b32_e32 v23, 0xffff, v15
	v_lshrrev_b32_e32 v15, 16, v15
	v_and_b32_e32 v24, 0xffff, v16
	v_lshrrev_b32_e32 v16, 16, v16
	v_and_b32_e32 v25, 0xffff, v17
	v_lshrrev_b32_e32 v17, 16, v17
	s_waitcnt vmcnt(2)
	v_lshl_or_b32 v22, v18, 16, v22
	v_and_or_b32 v14, v18, s4, v14
	v_lshl_or_b32 v18, v19, 16, v23
	v_and_or_b32 v15, v19, s4, v15
	v_lshl_or_b32 v19, v20, 16, v24
	v_and_or_b32 v16, v20, s4, v16
	v_lshl_or_b32 v20, v21, 16, v25
	v_and_or_b32 v17, v21, s4, v17
	ds_write2_b32 v0, v22, v14 offset1:68
	ds_write2_b32 v0, v18, v15 offset0:136 offset1:204
	ds_write2_b32 v13, v19, v16 offset0:16 offset1:84
	ds_write2_b32 v13, v20, v17 offset0:152 offset1:220
	s_waitcnt vmcnt(1)
	v_and_b32_e32 v38, 0xffff, v28
	v_lshrrev_b32_e32 v28, 16, v28
	v_and_b32_e32 v39, 0xffff, v29
	v_lshrrev_b32_e32 v29, 16, v29
	v_and_b32_e32 v40, 0xffff, v30
	v_lshrrev_b32_e32 v30, 16, v30
	v_and_b32_e32 v41, 0xffff, v31
	v_lshrrev_b32_e32 v31, 16, v31
	s_waitcnt vmcnt(0)
	v_lshl_or_b32 v38, v32, 16, v38
	v_and_or_b32 v28, v32, s4, v28
	v_lshl_or_b32 v32, v33, 16, v39
	v_and_or_b32 v29, v33, s4, v29
	v_lshl_or_b32 v33, v34, 16, v40
	v_and_or_b32 v30, v34, s4, v30
	v_lshl_or_b32 v34, v35, 16, v41
	v_and_or_b32 v31, v35, s4, v31
	ds_write2_b32 v26, v38, v28 offset1:68
	ds_write2_b32 v26, v32, v29 offset0:136 offset1:204
	ds_write2_b32 v27, v33, v30 offset0:16 offset1:84
	ds_write2_b32 v27, v34, v31 offset0:152 offset1:220
	s_waitcnt lgkmcnt(0)
	s_barrier
	s_and_saveexec_b64 s[0:1], s[6:7]
	s_cbranch_execz .LBB0_597
	global_load_dwordx4 v[12:15], v[2:3], off
	global_load_dwordx4 v[20:23], v[2:3], off offset:64
	ds_read_b128 v[16:19], v10
	ds_read_b128 v[24:27], v10 offset:64
	ds_read_b128 v[28:31], v10 offset:4352
	ds_read_b128 v[32:35], v10 offset:4416
	ds_read_b128 v[36:39], v10 offset:8704
	ds_read_b128 v[40:43], v10 offset:8768
	ds_read_b128 v[44:47], v10 offset:13056
	ds_read_b128 v[48:51], v10 offset:13120
	ds_read_b128 v[52:55], v10 offset:17408
	ds_read_b128 v[56:59], v10 offset:17472
	ds_read_b128 v[60:63], v10 offset:21760
	ds_read_b128 v[64:67], v10 offset:21824
	ds_read_b128 v[68:71], v10 offset:26112
	ds_read_b128 v[72:75], v10 offset:26176
	ds_read_b128 v[76:79], v10 offset:30464
	ds_read_b128 v[80:83], v10 offset:30528
	v_or_b32_e32 v0, s11, v7
	v_lshlrev_b32_e32 v0, 1, v0
	v_mov_b32_e32 v5, v1
	s_waitcnt vmcnt(1) lgkmcnt(14)
	v_mfma_f32_16x16x32_bf16 v[16:19], v[16:19], v[12:15], 0
	s_waitcnt lgkmcnt(13)
	v_mfma_f32_16x16x32_bf16 v[28:31], v[28:31], v[12:15], 0
	s_waitcnt lgkmcnt(11)
	v_mfma_f32_16x16x32_bf16 v[36:39], v[36:39], v[12:15], 0
	s_waitcnt vmcnt(0)
	v_mfma_f32_16x16x32_bf16 v[16:19], v[24:27], v[20:23], v[16:19]
	v_mfma_f32_16x16x32_bf16 v[24:27], v[32:35], v[20:23], v[28:31]
	s_waitcnt lgkmcnt(10)
	v_mfma_f32_16x16x32_bf16 v[28:31], v[40:43], v[20:23], v[36:39]
	global_load_dwordx4 v[40:43], v[2:3], off offset:128
	s_waitcnt lgkmcnt(9)
	v_mfma_f32_16x16x32_bf16 v[44:47], v[44:47], v[12:15], 0
	s_waitcnt lgkmcnt(8)
	v_mfma_f32_16x16x32_bf16 v[32:35], v[48:51], v[20:23], v[44:47]
	global_load_dwordx4 v[48:51], v[2:3], off offset:192
	s_waitcnt lgkmcnt(7)
	v_mfma_f32_16x16x32_bf16 v[52:55], v[52:55], v[12:15], 0
	s_waitcnt lgkmcnt(6)
	v_mfma_f32_16x16x32_bf16 v[36:39], v[56:59], v[20:23], v[52:55]
	ds_read_b128 v[56:59], v10 offset:128
	s_waitcnt lgkmcnt(6)
	v_mfma_f32_16x16x32_bf16 v[60:63], v[60:63], v[12:15], 0
	s_waitcnt lgkmcnt(4)
	v_mfma_f32_16x16x32_bf16 v[68:71], v[68:71], v[12:15], 0
	s_waitcnt lgkmcnt(2)
	v_mfma_f32_16x16x32_bf16 v[12:15], v[76:79], v[12:15], 0
	v_mfma_f32_16x16x32_bf16 v[44:47], v[64:67], v[20:23], v[60:63]
	v_mfma_f32_16x16x32_bf16 v[52:55], v[72:75], v[20:23], v[68:71]
	s_waitcnt lgkmcnt(1)
	v_mfma_f32_16x16x32_bf16 v[12:15], v[80:83], v[20:23], v[12:15]
	ds_read_b128 v[20:23], v10 offset:4480
	ds_read_b128 v[60:63], v10 offset:192
	s_waitcnt vmcnt(1) lgkmcnt(2)
	v_mfma_f32_16x16x32_bf16 v[16:19], v[56:59], v[40:43], v[16:19]
	ds_read_b128 v[56:59], v10 offset:8832
	ds_read_b128 v[64:67], v10 offset:4544
	s_waitcnt lgkmcnt(3)
	v_mfma_f32_16x16x32_bf16 v[20:23], v[20:23], v[40:43], v[24:27]
	s_nop 2
	ds_read_b128 v[24:27], v10 offset:13184
	ds_read_b128 v[68:71], v10 offset:8896
	s_waitcnt lgkmcnt(3)
	v_mfma_f32_16x16x32_bf16 v[28:31], v[56:59], v[40:43], v[28:31]
	ds_read_b128 v[56:59], v10 offset:17536
	ds_read_b128 v[72:75], v10 offset:21888
	ds_read_b128 v[76:79], v10 offset:13248
	s_waitcnt lgkmcnt(4)
	v_mfma_f32_16x16x32_bf16 v[24:27], v[24:27], v[40:43], v[32:35]
	s_nop 2
	ds_read_b128 v[32:35], v10 offset:26240
	ds_read_b128 v[80:83], v10 offset:17600
	ds_read_b128 v[84:87], v10 offset:21952
	s_waitcnt lgkmcnt(5)
	v_mfma_f32_16x16x32_bf16 v[36:39], v[56:59], v[40:43], v[36:39]
	ds_read_b128 v[56:59], v10 offset:26304
	ds_read_b128 v[88:91], v10 offset:30592
	ds_read_b128 v[92:95], v10 offset:30656
	s_waitcnt lgkmcnt(7)
	v_mfma_f32_16x16x32_bf16 v[44:47], v[72:75], v[40:43], v[44:47]
	v_or_b32_e32 v72, s10, v6
	v_ashrrev_i32_e32 v73, 31, v72
	s_waitcnt vmcnt(0)
	v_mfma_f32_16x16x32_bf16 v[16:19], v[60:63], v[48:51], v[16:19]
	s_waitcnt lgkmcnt(5)
	v_mfma_f32_16x16x32_bf16 v[32:35], v[32:35], v[40:43], v[52:55]
	s_nop 2
	v_lshlrev_b64 v[52:53], 11, v[72:73]
	v_lshl_add_u64 v[52:53], s[58:59], 0, v[52:53]
	s_waitcnt lgkmcnt(1)
	v_mfma_f32_16x16x32_bf16 v[12:15], v[88:91], v[40:43], v[12:15]
	v_lshl_add_u64 v[40:41], v[52:53], 0, v[0:1]
	v_lshl_add_u64 v[40:41], v[40:41], 0, v[4:5]
	v_cvt_pk_bf16_f32 v16, v16, v17
	v_cvt_pk_bf16_f32 v17, v18, v19
	global_store_dwordx2 v[40:41], v[16:17], off
	v_mfma_f32_16x16x32_bf16 v[16:19], v[64:67], v[48:51], v[20:23]
	s_waitcnt lgkmcnt(0)
	v_mfma_f32_16x16x32_bf16 v[12:15], v[92:95], v[48:51], v[12:15]
	s_nop 5
	v_cvt_pk_bf16_f32 v16, v16, v17
	v_cvt_pk_bf16_f32 v17, v18, v19
	global_store_dwordx2 v[40:41], v[16:17], off offset:32
	v_mfma_f32_16x16x32_bf16 v[16:19], v[68:71], v[48:51], v[28:31]
	v_cvt_pk_bf16_f32 v12, v12, v13
	v_cvt_pk_bf16_f32 v13, v14, v15
	global_store_dwordx2 v[40:41], v[12:13], off offset:224
	s_nop 4
	v_cvt_pk_bf16_f32 v16, v16, v17
	v_cvt_pk_bf16_f32 v17, v18, v19
	global_store_dwordx2 v[40:41], v[16:17], off offset:64
	v_mfma_f32_16x16x32_bf16 v[16:19], v[76:79], v[48:51], v[24:27]
	s_nop 7
	v_cvt_pk_bf16_f32 v16, v16, v17
	v_cvt_pk_bf16_f32 v17, v18, v19
	global_store_dwordx2 v[40:41], v[16:17], off offset:96
	v_mfma_f32_16x16x32_bf16 v[16:19], v[80:83], v[48:51], v[36:39]
	s_nop 7
	v_cvt_pk_bf16_f32 v16, v16, v17
	v_cvt_pk_bf16_f32 v17, v18, v19
	global_store_dwordx2 v[40:41], v[16:17], off offset:128
	v_mfma_f32_16x16x32_bf16 v[16:19], v[84:87], v[48:51], v[44:47]
	s_nop 7
	v_cvt_pk_bf16_f32 v16, v16, v17
	v_cvt_pk_bf16_f32 v17, v18, v19
	global_store_dwordx2 v[40:41], v[16:17], off offset:160
	v_mfma_f32_16x16x32_bf16 v[16:19], v[56:59], v[48:51], v[32:35]
	s_nop 7
	v_cvt_pk_bf16_f32 v16, v16, v17
	v_cvt_pk_bf16_f32 v17, v18, v19
	global_store_dwordx2 v[40:41], v[16:17], off offset:192
	s_branch .LBB0_597

.LBB0_759:
	s_lshl_b32 s1, s97, 4
	s_bfe_u32 s0, s97, 0x60002
	s_and_b32 s1, s1, 0xfffff000
	s_or_b32 s6, s1, s0
	s_lshl_b32 s0, s97, 9
	s_addk_i32 s6, 0x2000
	s_and_b32 s0, s0, 0x600
	s_add_u32 s0, s58, s0
	s_addc_u32 s1, s59, 0
	s_mov_b64 s[10:11], 0
	v_mov_b32_e32 v5, v8
	v_mov_b32_e32 v10, v101
	v_mov_b32_e32 v11, v7
	v_and_b32_e32 v20, 62, v5
	v_lshl_or_b32 v12, v20, 6, s6
	v_ashrrev_i32_e32 v13, 31, v12
	v_and_b32_e32 v21, 0x80, v10
	v_lshlrev_b64 v[12:13], 11, v[12:13]
	v_and_b32_e32 v22, 0x78, v10
	v_lshlrev_b32_e32 v0, 1, v21
	v_lshl_add_u64 v[12:13], s[0:1], 0, v[12:13]
	v_lshl_add_u64 v[12:13], v[12:13], 0, v[0:1]
	v_lshlrev_b32_e32 v0, 1, v22
	v_lshl_add_u64 v[36:37], v[12:13], 0, v[0:1]
	v_add_co_u32_e32 v38, vcc, s4, v36
	v_mad_u32_u24 v0, v22, s3, 0
	s_nop 0
	v_addc_co_u32_e32 v39, vcc, 0, v37, vcc
	global_load_dwordx4 v[12:15], v[36:37], off
	global_load_dwordx4 v[16:19], v[38:39], off
	global_load_dwordx4 v[28:31], v[36:37], off offset:256
	global_load_dwordx4 v[32:35], v[38:39], off offset:256
	v_lshlrev_b32_e32 v20, 1, v20
	v_add3_u32 v0, v0, v21, v20
	v_add_u32_e32 v20, 0x400, v0
	v_add_u32_e32 v26, 0x80, v0
	v_add_u32_e32 v27, 0x480, v0
	s_waitcnt vmcnt(3)
	v_and_b32_e32 v21, 0xffff, v12
	v_lshrrev_b32_e32 v12, 16, v12
	v_and_b32_e32 v22, 0xffff, v13
	v_lshrrev_b32_e32 v13, 16, v13
	v_and_b32_e32 v23, 0xffff, v14
	v_lshrrev_b32_e32 v14, 16, v14
	v_and_b32_e32 v24, 0xffff, v15
	v_lshrrev_b32_e32 v15, 16, v15
	s_waitcnt vmcnt(2)
	v_lshl_or_b32 v21, v16, 16, v21
	v_and_or_b32 v12, v16, s5, v12
	v_lshl_or_b32 v16, v17, 16, v22
	v_and_or_b32 v13, v17, s5, v13
	v_lshl_or_b32 v17, v18, 16, v23
	v_and_or_b32 v14, v18, s5, v14
	v_lshl_or_b32 v18, v19, 16, v24
	v_and_or_b32 v15, v19, s5, v15
	ds_write2_b32 v0, v21, v12 offset1:68
	ds_write2_b32 v0, v16, v13 offset0:136 offset1:204
	ds_write2_b32 v20, v17, v14 offset0:16 offset1:84
	ds_write2_b32 v20, v18, v15 offset0:152 offset1:220
	s_waitcnt vmcnt(1)
	v_and_b32_e32 v40, 0xffff, v28
	v_lshrrev_b32_e32 v28, 16, v28
	v_and_b32_e32 v41, 0xffff, v29
	v_lshrrev_b32_e32 v29, 16, v29
	v_and_b32_e32 v42, 0xffff, v30
	v_lshrrev_b32_e32 v30, 16, v30
	v_and_b32_e32 v43, 0xffff, v31
	v_lshrrev_b32_e32 v31, 16, v31
	s_waitcnt vmcnt(0)
	v_lshl_or_b32 v40, v32, 16, v40
	v_and_or_b32 v28, v32, s5, v28
	v_lshl_or_b32 v32, v33, 16, v41
	v_and_or_b32 v29, v33, s5, v29
	v_lshl_or_b32 v33, v34, 16, v42
	v_and_or_b32 v30, v34, s5, v30
	v_lshl_or_b32 v34, v35, 16, v43
	v_and_or_b32 v31, v35, s5, v31
	ds_write2_b32 v26, v40, v28 offset1:68
	ds_write2_b32 v26, v32, v29 offset0:136 offset1:204
	ds_write2_b32 v27, v33, v30 offset0:16 offset1:84
	ds_write2_b32 v27, v34, v31 offset0:152 offset1:220
	s_waitcnt lgkmcnt(0)
	s_barrier
	s_and_saveexec_b64 s[10:11], s[8:9]
	s_cbranch_execz .LBB0_758
	global_load_dwordx4 v[10:13], v[2:3], off
	global_load_dwordx4 v[18:21], v[2:3], off offset:64
	ds_read_b128 v[14:17], v9
	ds_read_b128 v[22:25], v9 offset:64
	ds_read_b128 v[26:29], v9 offset:4352
	ds_read_b128 v[30:33], v9 offset:4416
	ds_read_b128 v[34:37], v9 offset:8704
	ds_read_b128 v[38:41], v9 offset:8768
	ds_read_b128 v[42:45], v9 offset:13056
	ds_read_b128 v[46:49], v9 offset:13120
	ds_read_b128 v[50:53], v9 offset:17408
	ds_read_b128 v[54:57], v9 offset:17472
	ds_read_b128 v[58:61], v9 offset:21760
	ds_read_b128 v[62:65], v9 offset:21824
	ds_read_b128 v[66:69], v9 offset:26112
	ds_read_b128 v[70:73], v9 offset:26176
	ds_read_b128 v[74:77], v9 offset:30464
	ds_read_b128 v[78:81], v9 offset:30528
	v_or_b32_e32 v88, s6, v6
	v_mov_b32_e32 v5, v1
	v_ashrrev_i32_e32 v89, 31, v88
	v_lshl_add_u64 v[86:87], s[0:1], 0, v[4:5]
	s_waitcnt vmcnt(1) lgkmcnt(14)
	v_mfma_f32_16x16x32_bf16 v[14:17], v[14:17], v[10:13], 0
	s_waitcnt lgkmcnt(13)
	v_mfma_f32_16x16x32_bf16 v[26:29], v[26:29], v[10:13], 0
	s_waitcnt lgkmcnt(11)
	v_mfma_f32_16x16x32_bf16 v[34:37], v[34:37], v[10:13], 0
	s_waitcnt vmcnt(0)
	v_mfma_f32_16x16x32_bf16 v[14:17], v[22:25], v[18:21], v[14:17]
	v_mfma_f32_16x16x32_bf16 v[22:25], v[30:33], v[18:21], v[26:29]
	s_waitcnt lgkmcnt(10)
	v_mfma_f32_16x16x32_bf16 v[26:29], v[38:41], v[18:21], v[34:37]
	global_load_dwordx4 v[38:41], v[2:3], off offset:128
	s_waitcnt lgkmcnt(9)
	v_mfma_f32_16x16x32_bf16 v[42:45], v[42:45], v[10:13], 0
	s_waitcnt lgkmcnt(8)
	v_mfma_f32_16x16x32_bf16 v[30:33], v[46:49], v[18:21], v[42:45]
	global_load_dwordx4 v[46:49], v[2:3], off offset:192
	s_waitcnt lgkmcnt(7)
	v_mfma_f32_16x16x32_bf16 v[50:53], v[50:53], v[10:13], 0
	s_waitcnt lgkmcnt(6)
	v_mfma_f32_16x16x32_bf16 v[34:37], v[54:57], v[18:21], v[50:53]
	ds_read_b128 v[54:57], v9 offset:128
	s_waitcnt lgkmcnt(6)
	v_mfma_f32_16x16x32_bf16 v[58:61], v[58:61], v[10:13], 0
	s_waitcnt lgkmcnt(4)
	v_mfma_f32_16x16x32_bf16 v[66:69], v[66:69], v[10:13], 0
	s_waitcnt lgkmcnt(2)
	v_mfma_f32_16x16x32_bf16 v[10:13], v[74:77], v[10:13], 0
	v_mfma_f32_16x16x32_bf16 v[42:45], v[62:65], v[18:21], v[58:61]
	v_mfma_f32_16x16x32_bf16 v[50:53], v[70:73], v[18:21], v[66:69]
	s_waitcnt lgkmcnt(1)
	v_mfma_f32_16x16x32_bf16 v[10:13], v[78:81], v[18:21], v[10:13]
	ds_read_b128 v[18:21], v9 offset:4480
	ds_read_b128 v[58:61], v9 offset:192
	s_waitcnt vmcnt(1) lgkmcnt(2)
	v_mfma_f32_16x16x32_bf16 v[14:17], v[54:57], v[38:41], v[14:17]
	ds_read_b128 v[54:57], v9 offset:8832
	ds_read_b128 v[62:65], v9 offset:4544
	s_waitcnt lgkmcnt(3)
	v_mfma_f32_16x16x32_bf16 v[18:21], v[18:21], v[38:41], v[22:25]
	s_nop 2
	ds_read_b128 v[22:25], v9 offset:13184
	ds_read_b128 v[66:69], v9 offset:8896
	s_waitcnt lgkmcnt(3)
	v_mfma_f32_16x16x32_bf16 v[26:29], v[54:57], v[38:41], v[26:29]
	ds_read_b128 v[54:57], v9 offset:17536
	ds_read_b128 v[70:73], v9 offset:13248
	s_waitcnt lgkmcnt(3)
	v_mfma_f32_16x16x32_bf16 v[22:25], v[22:25], v[38:41], v[30:33]
	s_nop 2
	ds_read_b128 v[30:33], v9 offset:21888
	ds_read_b128 v[74:77], v9 offset:17600
	s_waitcnt lgkmcnt(3)
	v_mfma_f32_16x16x32_bf16 v[34:37], v[54:57], v[38:41], v[34:37]
	ds_read_b128 v[54:57], v9 offset:26240
	ds_read_b128 v[78:81], v9 offset:21952
	ds_read_b128 v[82:85], v9 offset:26304
	s_waitcnt lgkmcnt(4)
	v_mfma_f32_16x16x32_bf16 v[30:33], v[30:33], v[38:41], v[42:45]
	s_nop 2
	ds_read_b128 v[42:45], v9 offset:30592
	s_waitcnt vmcnt(0)
	v_mfma_f32_16x16x32_bf16 v[14:17], v[58:61], v[46:49], v[14:17]
	s_waitcnt lgkmcnt(3)
	v_mfma_f32_16x16x32_bf16 v[50:53], v[54:57], v[38:41], v[50:53]
	ds_read_b128 v[54:57], v9 offset:30656
	s_nop 4
	v_cvt_pk_bf16_f32 v14, v14, v15
	v_cvt_pk_bf16_f32 v15, v16, v17
	s_waitcnt lgkmcnt(1)
	v_mfma_f32_16x16x32_bf16 v[10:13], v[42:45], v[38:41], v[10:13]
	v_lshlrev_b64 v[38:39], 11, v[88:89]
	v_lshl_add_u64 v[38:39], v[86:87], 0, v[38:39]
	global_store_dwordx2 v[38:39], v[14:15], off
	v_mfma_f32_16x16x32_bf16 v[14:17], v[62:65], v[46:49], v[18:21]
	s_waitcnt lgkmcnt(0)
	v_mfma_f32_16x16x32_bf16 v[10:13], v[54:57], v[46:49], v[10:13]
	s_nop 5
	v_cvt_pk_bf16_f32 v14, v14, v15
	v_cvt_pk_bf16_f32 v15, v16, v17
	global_store_dwordx2 v[38:39], v[14:15], off offset:32
	v_mfma_f32_16x16x32_bf16 v[14:17], v[66:69], v[46:49], v[26:29]
	v_cvt_pk_bf16_f32 v10, v10, v11
	v_cvt_pk_bf16_f32 v11, v12, v13
	global_store_dwordx2 v[38:39], v[10:11], off offset:224
	s_nop 4
	v_cvt_pk_bf16_f32 v14, v14, v15
	v_cvt_pk_bf16_f32 v15, v16, v17
	global_store_dwordx2 v[38:39], v[14:15], off offset:64
	v_mfma_f32_16x16x32_bf16 v[14:17], v[70:73], v[46:49], v[22:25]
	s_nop 7
	v_cvt_pk_bf16_f32 v14, v14, v15
	v_cvt_pk_bf16_f32 v15, v16, v17
	global_store_dwordx2 v[38:39], v[14:15], off offset:96
	v_mfma_f32_16x16x32_bf16 v[14:17], v[74:77], v[46:49], v[34:37]
	s_nop 7
	v_cvt_pk_bf16_f32 v14, v14, v15
	v_cvt_pk_bf16_f32 v15, v16, v17
	global_store_dwordx2 v[38:39], v[14:15], off offset:128
	v_mfma_f32_16x16x32_bf16 v[14:17], v[78:81], v[46:49], v[30:33]
	s_nop 7
	v_cvt_pk_bf16_f32 v14, v14, v15
	v_cvt_pk_bf16_f32 v15, v16, v17
	global_store_dwordx2 v[38:39], v[14:15], off offset:160
	v_mfma_f32_16x16x32_bf16 v[14:17], v[82:85], v[46:49], v[50:53]
	s_nop 7
	v_cvt_pk_bf16_f32 v14, v14, v15
	v_cvt_pk_bf16_f32 v15, v16, v17
	global_store_dwordx2 v[38:39], v[14:15], off offset:192
	s_branch .LBB0_758
